# k11 + GEMM phase prologue: K-tile 1 LDS-DMA loads issued before the first counted wait (vmcnt 2 -> 8), 18 phases
# speedup vs baseline: 1.0118x; 1.0016x over previous
.LBB0_192:
	s_add_u32 s12, s72, 0x9400000
	s_addc_u32 s13, s73, 0
	s_lshl_b32 s5, s5, 5
	s_mov_b64 s[14:15], 0x80
	s_and_b32 s5, s5, 0x60
	s_add_i32 m0, s27, 0x18000
	v_lshl_add_u64 v[10:11], v[10:11], 0, s[14:15]
	s_lshl_b32 s8, s1, 13
	s_lshl_b32 s18, s5, 7
	global_load_lds_dwordx4 v[10:11], off
	v_lshl_add_u64 v[8:9], v[8:9], 0, s[14:15]
	s_add_i32 m0, s27, 0x1a000
	s_add_i32 s40, s27, 0x8000
	s_add_i32 s41, s27, 0xa000
	global_load_lds_dwordx4 v[8:9], off
	v_lshl_add_u64 v[4:5], v[4:5], 0, s[14:15]
	s_mov_b32 m0, s40
	s_add_u32 s16, s2, 0x40080
	global_load_lds_dwordx4 v[4:5], off
	v_lshl_add_u64 v[4:5], v[6:7], 0, s[14:15]
	s_mov_b32 m0, s41
	s_addc_u32 s17, s3, 0
	global_load_lds_dwordx4 v[4:5], off
	s_add_i32 m0, s27, 0x1c000
	v_lshl_add_u64 v[4:5], s[16:17], 0, v[132:133]
	global_load_lds_dwordx4 v[4:5], off
	v_lshl_add_u64 v[4:5], s[16:17], 0, v[136:137]
	s_add_i32 m0, s27, 0x1e000
	v_lshlrev_b32_e32 v6, 2, v0
	global_load_lds_dwordx4 v[4:5], off
	v_and_b32_e32 v4, 15, v0
	v_lshl_or_b32 v165, s1, 6, v4
	v_lshlrev_b32_e32 v5, 1, v2
	v_lshlrev_b32_e32 v7, 6, v0
	s_movk_i32 s1, 0x3c0
	v_lshl_or_b32 v4, v4, 6, v5
	v_and_b32_e32 v6, 32, v6
	v_and_or_b32 v5, v7, s1, v5
	v_bitop3_b32 v166, s18, v5, v6 bitop3:0xf6
	v_lshlrev_b32_e32 v5, 8, v0
	v_bitop3_b32 v4, v4, s8, v6 bitop3:0xde
	v_and_b32_e32 v5, 0x18000, v5
	v_lshlrev_b32_e32 v6, 11, v13
	v_or3_b32 v5, v3, v5, v6
	v_add_u32_e32 v140, v5, v12
	v_lshlrev_b32_e32 v5, 4, v14
	s_waitcnt vmcnt(8)
	s_barrier
	s_waitcnt vmcnt(6)
	s_cmpk_lt_u32 s0, 0x100
	v_and_b32_e32 v5, 0x38000, v5
	s_cselect_b64 s[16:17], -1, 0
	v_or3_b32 v3, v3, v5, v6
	s_add_i32 s43, 0, 0x10000
	s_add_i32 s44, 0, 0x14000
	s_sext_i32_i8 s46, s4
	s_ashr_i32 s42, s75, 31
	v_mov_b32_e32 v141, v139
	v_add_u32_e32 v142, v3, v12
	v_mov_b32_e32 v143, v139
	v_mov_b64_e32 v[144:145], 0x200
	v_mov_b64_e32 v[146:147], 0x1ff
	v_add_u32_e32 v167, s43, v166
	v_add_u32_e32 v168, s44, v166
	v_add_u32_e32 v169, 0, v4
	v_mov_b32_e32 v170, 0x358637bd
	s_lshl_b32 s8, s5, 1
	v_lshlrev_b32_e32 v138, 1, v2
	s_mov_b32 s45, s9
	s_barrier
	s_branch .LBB0_195

.LBB0_273:
	s_add_u32 s18, s72, 0x9400000
	s_addc_u32 s19, s73, 0
	s_add_u32 s20, s72, 0xb400000
	s_addc_u32 s21, s73, 0
	s_lshl_b32 s4, s4, 5
	s_mov_b64 s[22:23], 0x80
	s_and_b32 s9, s4, 0x60
	s_add_i32 m0, s40, 0x18000
	v_lshl_add_u64 v[8:9], v[8:9], 0, s[22:23]
	s_lshl_b32 s7, s1, 13
	s_lshl_b32 s12, s9, 7
	global_load_lds_dwordx4 v[8:9], off
	v_lshl_add_u64 v[6:7], v[6:7], 0, s[22:23]
	s_add_i32 m0, s40, 0x1a000
	s_add_i32 s45, s40, 0x8000
	s_add_i32 s46, s40, 0xa000
	global_load_lds_dwordx4 v[6:7], off
	v_lshl_add_u64 v[2:3], v[2:3], 0, s[22:23]
	s_mov_b32 m0, s45
	s_add_u32 s4, s2, 0x40080
	global_load_lds_dwordx4 v[2:3], off
	v_lshl_add_u64 v[2:3], v[4:5], 0, s[22:23]
	s_mov_b32 m0, s46
	s_addc_u32 s5, s3, 0
	global_load_lds_dwordx4 v[2:3], off
	s_add_i32 m0, s40, 0x1c000
	v_lshl_add_u64 v[2:3], s[4:5], 0, v[172:173]
	global_load_lds_dwordx4 v[2:3], off
	v_lshl_add_u64 v[2:3], s[4:5], 0, v[176:177]
	s_add_i32 m0, s40, 0x1e000
	v_lshlrev_b32_e32 v4, 2, v0
	global_load_lds_dwordx4 v[2:3], off
	v_and_b32_e32 v2, 15, v0
	v_lshl_or_b32 v222, s1, 6, v2
	v_lshlrev_b32_e32 v3, 1, v14
	v_lshlrev_b32_e32 v6, 6, v0
	s_movk_i32 s1, 0x3c0
	v_lshl_or_b32 v2, v2, 6, v3
	v_and_b32_e32 v5, 32, v4
	v_and_or_b32 v3, v6, s1, v3
	s_cmpk_lt_u32 s0, 0x100
	v_bitop3_b32 v223, s12, v3, v5 bitop3:0xf6
	s_cselect_b64 s[24:25], -1, 0
	s_add_i32 s0, 0, 0x20000
	v_lshlrev_b32_e32 v3, 8, v0
	v_add_u32_e32 v225, s0, v4
	v_and_b32_e32 v3, 0x18000, v3
	v_lshlrev_b32_e32 v4, 11, v12
	v_or3_b32 v3, v10, v3, v4
	v_add_u32_e32 v180, v3, v11
	v_lshlrev_b32_e32 v3, 4, v13
	s_waitcnt vmcnt(8)
	s_barrier
	s_waitcnt vmcnt(6)
	v_or_b32_e32 v178, s9, v14
	v_and_b32_e32 v3, 0x38000, v3
	v_bitop3_b32 v2, v2, s7, v5 bitop3:0xde
	v_or_b32_e32 v224, 0x80, v178
	v_or3_b32 v3, v10, v3, v4
	s_add_i32 s49, 0, 0x10000
	s_add_i32 s50, 0, 0x14000
	s_ashr_i32 s47, s75, 31
	s_ashr_i32 s48, s64, 31
	v_lshl_add_u32 v226, v178, 2, s0
	v_lshl_add_u32 v227, v224, 2, s0
	v_mov_b32_e32 v179, v173
	v_mov_b32_e32 v181, v173
	v_add_u32_e32 v182, v3, v11
	v_mov_b32_e32 v183, v173
	v_mov_b64_e32 v[184:185], 0x100
	v_mov_b64_e32 v[186:187], 0xff
	v_add_u32_e32 v228, s49, v223
	v_add_u32_e32 v229, s50, v223
	v_add_u32_e32 v230, 0, v2
	v_mov_b32_e32 v231, 0x358637bd
	s_barrier
	s_branch .LBB0_276

.LBB0_372:
	v_and_b32_e32 v14, 15, v0
	v_bfe_u32 v15, v0, 4, 2
	v_lshl_or_b32 v206, s4, 6, v14
	v_lshlrev_b32_e32 v17, 4, v15
	v_lshlrev_b32_e32 v18, 2, v206
	v_lshl_or_b32 v14, v14, 6, v17
	s_lshl_b32 s4, s4, 13
	v_and_b32_e32 v19, 32, v18
	v_bitop3_b32 v14, v14, s4, v19 bitop3:0xde
	v_lshlrev_b32_e32 v19, 6, v0
	s_movk_i32 s4, 0x3c0
	s_mov_b64 s[14:15], 0x80
	s_and_b32 s1, s1, 3
	v_and_or_b32 v17, v19, s4, v17
	v_lshlrev_b32_e32 v19, 2, v0
	s_add_i32 m0, s27, 0x18000
	v_lshl_add_u64 v[8:9], v[8:9], 0, s[14:15]
	s_lshl_b32 s4, s1, 12
	v_and_b32_e32 v20, 32, v19
	global_load_lds_dwordx4 v[8:9], off
	v_lshl_add_u64 v[6:7], v[6:7], 0, s[14:15]
	s_add_i32 m0, s27, 0x1a000
	s_add_i32 s42, s27, 0x8000
	s_add_i32 s43, s27, 0xa000
	v_bitop3_b32 v207, s4, v17, v20 bitop3:0xf6
	global_load_lds_dwordx4 v[6:7], off
	v_lshl_add_u64 v[2:3], v[2:3], 0, s[14:15]
	s_mov_b32 m0, s42
	s_add_u32 s4, s2, 0x40080
	global_load_lds_dwordx4 v[2:3], off
	v_lshl_add_u64 v[2:3], v[4:5], 0, s[14:15]
	s_mov_b32 m0, s43
	s_addc_u32 s5, s3, 0
	global_load_lds_dwordx4 v[2:3], off
	s_add_i32 m0, s27, 0x1c000
	v_lshl_add_u64 v[2:3], s[4:5], 0, v[180:181]
	global_load_lds_dwordx4 v[2:3], off
	v_lshl_add_u64 v[2:3], s[4:5], 0, v[184:185]
	s_add_i32 m0, s27, 0x1e000
	v_lshlrev_b32_e32 v16, 3, v15
	global_load_lds_dwordx4 v[2:3], off
	v_lshlrev_b32_e32 v2, 8, v0
	v_and_b32_e32 v2, 0x18000, v2
	v_lshlrev_b32_e32 v3, 11, v12
	v_or3_b32 v2, v10, v2, v3
	v_add_u32_e32 v186, v2, v11
	v_lshlrev_b32_e32 v2, 4, v13
	s_cmpk_lt_u32 s0, 0x100
	v_and_b32_e32 v2, 0x38000, v2
	s_waitcnt vmcnt(8)
	s_barrier
	s_waitcnt vmcnt(6)
	v_lshl_or_b32 v208, s1, 5, v16
	s_cselect_b64 s[16:17], -1, 0
	s_lshl_b32 s0, s1, 10
	s_add_i32 s1, 0, 0x20000
	v_or3_b32 v2, v10, v2, v3
	s_add_i32 s0, s1, s0
	v_add_u32_e32 v188, v2, v11
	s_add_i32 s46, 0, 0x10000
	s_add_i32 s47, 0, 0x14000
	v_mbcnt_lo_u32_b32 v2, -1, 0
	v_cmp_eq_u32_e64 s[4:5], 0, v15
	s_ashr_i32 s44, s75, 31
	s_ashr_i32 s45, s64, 31
	v_add_u32_e32 v209, s0, v18
	v_add_u32_e32 v210, s1, v19
	v_mov_b32_e32 v187, v181
	v_mov_b32_e32 v189, v181
	v_mov_b64_e32 v[190:191], 0x100
	v_mov_b64_e32 v[192:193], 0xff
	v_add_u32_e32 v211, s46, v207
	v_add_u32_e32 v212, s47, v207
	v_add_u32_e32 v213, 0, v14
	v_mbcnt_hi_u32_b32 v214, -1, v2
	s_barrier
	s_branch .LBB0_375

.LBB0_465:
	s_add_u32 s12, s72, 0x9400000
	v_and_b32_e32 v15, 15, v0
	v_lshlrev_b32_e32 v16, 1, v2
	s_sext_i32_i8 s27, s4
	s_addc_u32 s13, s73, 0
	v_lshl_or_b32 v165, s5, 6, v15
	v_lshl_or_b32 v15, v15, 6, v16
	s_lshl_b32 s4, s5, 13
	v_and_b32_e32 v17, 32, v164
	s_lshl_b32 s1, s1, 5
	s_mov_b64 s[14:15], 0x80
	v_bitop3_b32 v15, v15, s4, v17 bitop3:0xde
	s_and_b32 s1, s1, 0x60
	v_lshlrev_b32_e32 v18, 6, v0
	s_movk_i32 s4, 0x3c0
	s_add_i32 m0, s38, 0x18000
	v_lshl_add_u64 v[10:11], v[10:11], 0, s[14:15]
	v_and_or_b32 v16, v18, s4, v16
	s_lshl_b32 s4, s1, 7
	global_load_lds_dwordx4 v[10:11], off
	v_lshl_add_u64 v[8:9], v[8:9], 0, s[14:15]
	s_add_i32 m0, s38, 0x1a000
	s_add_i32 s42, s38, 0x8000
	s_add_i32 s43, s38, 0xa000
	v_bitop3_b32 v166, s4, v16, v17 bitop3:0xf6
	global_load_lds_dwordx4 v[8:9], off
	v_lshl_add_u64 v[4:5], v[4:5], 0, s[14:15]
	s_mov_b32 m0, s42
	s_add_u32 s4, s2, 0x40080
	global_load_lds_dwordx4 v[4:5], off
	v_lshl_add_u64 v[4:5], v[6:7], 0, s[14:15]
	s_mov_b32 m0, s43
	s_addc_u32 s5, s3, 0
	global_load_lds_dwordx4 v[4:5], off
	s_add_i32 m0, s38, 0x1c000
	v_lshl_add_u64 v[4:5], s[4:5], 0, v[134:135]
	global_load_lds_dwordx4 v[4:5], off
	v_lshl_add_u64 v[4:5], s[4:5], 0, v[130:131]
	s_add_i32 m0, s38, 0x1e000
	v_lshlrev_b32_e32 v3, 4, v3
	global_load_lds_dwordx4 v[4:5], off
	v_lshlrev_b32_e32 v4, 8, v0
	s_waitcnt vmcnt(8)
	s_barrier
	s_waitcnt vmcnt(6)
	s_cmpk_lt_u32 s0, 0x100
	v_and_b32_e32 v4, 0x18000, v4
	v_lshlrev_b32_e32 v5, 11, v14
	v_and_b32_e32 v3, 0x38000, v3
	s_cselect_b64 s[16:17], -1, 0
	v_or3_b32 v4, v12, v4, v5
	v_or3_b32 v3, v12, v3, v5
	s_add_i32 s45, 0, 0x10000
	s_add_i32 s46, 0, 0x14000
	s_ashr_i32 s44, s75, 31
	v_add_u32_e32 v140, v4, v13
	v_mov_b32_e32 v141, v139
	v_add_u32_e32 v142, v3, v13
	v_mov_b32_e32 v143, v139
	v_mov_b64_e32 v[144:145], 0x580
	v_mov_b64_e32 v[146:147], 0x57f
	v_add_u32_e32 v167, s45, v166
	v_add_u32_e32 v168, s46, v166
	v_add_u32_e32 v169, 0, v15
	v_mov_b32_e32 v170, 0x358637bd
	s_movk_i32 s47, 0x1600
	s_lshl_b32 s8, s1, 1
	v_lshlrev_b32_e32 v138, 1, v2
	s_mov_b32 s48, s9
	s_barrier
	s_branch .LBB0_468

.LBB0_570:
	s_mov_b64 s[16:17], 0x80
	s_and_b32 s6, s4, 3
	s_add_i32 m0, s31, 0x18000
	v_lshl_add_u64 v[8:9], v[8:9], 0, s[16:17]
	s_lshl_b32 s7, s1, 13
	s_lshl_b32 s8, s6, 12
	global_load_lds_dwordx4 v[8:9], off
	v_lshl_add_u64 v[6:7], v[6:7], 0, s[16:17]
	s_add_i32 m0, s31, 0x1a000
	s_add_i32 s37, s31, 0x8000
	s_add_i32 s38, s31, 0xa000
	global_load_lds_dwordx4 v[6:7], off
	v_lshl_add_u64 v[2:3], v[2:3], 0, s[16:17]
	s_mov_b32 m0, s37
	s_add_u32 s4, s2, 0xb0080
	global_load_lds_dwordx4 v[2:3], off
	v_lshl_add_u64 v[2:3], v[4:5], 0, s[16:17]
	s_mov_b32 m0, s38
	s_addc_u32 s5, s3, 0
	global_load_lds_dwordx4 v[2:3], off
	s_add_i32 m0, s31, 0x1c000
	v_lshl_add_u64 v[2:3], s[4:5], 0, v[156:157]
	global_load_lds_dwordx4 v[2:3], off
	v_lshl_add_u64 v[2:3], s[4:5], 0, v[160:161]
	s_add_i32 m0, s31, 0x1e000
	s_cmpk_lt_u32 s0, 0x100
	global_load_lds_dwordx4 v[2:3], off
	v_and_b32_e32 v3, 15, v0
	v_bfe_u32 v2, v0, 4, 2
	v_lshl_or_b32 v182, s1, 6, v3
	v_lshlrev_b32_e32 v5, 4, v2
	v_lshlrev_b32_e32 v6, 2, v182
	v_lshl_or_b32 v3, v3, 6, v5
	v_and_b32_e32 v7, 32, v6
	v_bitop3_b32 v3, v3, s7, v7 bitop3:0xde
	v_lshlrev_b32_e32 v7, 6, v0
	s_movk_i32 s1, 0x3c0
	v_lshlrev_b32_e32 v4, 3, v2
	v_and_or_b32 v5, v7, s1, v5
	v_lshlrev_b32_e32 v7, 2, v0
	v_cmp_eq_u32_e64 s[4:5], 0, v2
	v_add_u16_e32 v2, v10, v11
	v_and_b32_e32 v8, 32, v7
	s_waitcnt vmcnt(8)
	s_barrier
	s_waitcnt vmcnt(6)
	s_cselect_b64 s[18:19], -1, 0
	s_lshl_b32 s0, s6, 10
	s_add_i32 s1, 0, 0x20000
	v_lshrrev_b16_e32 v2, 1, v2
	v_bitop3_b32 v183, s8, v5, v8 bitop3:0xf6
	s_add_i32 s0, s1, s0
	v_add_lshl_u32 v162, v12, v2, 1
	v_add_lshl_u32 v164, v13, v2, 1
	s_add_i32 s41, 0, 0x10000
	s_add_i32 s42, 0, 0x14000
	v_mbcnt_lo_u32_b32 v2, -1, 0
	v_lshl_or_b32 v184, s6, 5, v4
	s_ashr_i32 s39, s75, 31
	s_ashr_i32 s40, s64, 31
	v_add_u32_e32 v185, s0, v6
	v_add_u32_e32 v186, s1, v7
	v_mov_b32_e32 v163, v157
	v_mov_b32_e32 v165, v157
	v_mov_b64_e32 v[166:167], 0x100
	v_mov_b64_e32 v[168:169], 0xff
	v_add_u32_e32 v187, s41, v183
	v_add_u32_e32 v188, s42, v183
	v_add_u32_e32 v189, 0, v3
	v_mbcnt_hi_u32_b32 v190, -1, v2
	s_barrier
	s_branch .LBB0_573

.LBB0_669:
	s_add_u32 s41, s72, 0x9400000
	s_mov_b64 s[12:13], 0x80
	s_addc_u32 s42, s73, 0
	s_and_b32 s43, s4, 3
	s_add_i32 m0, s29, 0x18000
	v_lshl_add_u64 v[8:9], v[8:9], 0, s[12:13]
	s_lshl_b32 s7, s1, 13
	s_lshl_b32 s14, s43, 12
	global_load_lds_dwordx4 v[8:9], off
	v_lshl_add_u64 v[6:7], v[6:7], 0, s[12:13]
	s_add_i32 m0, s29, 0x1a000
	s_add_i32 s44, s29, 0x8000
	s_add_i32 s45, s29, 0xa000
	global_load_lds_dwordx4 v[6:7], off
	v_lshl_add_u64 v[2:3], v[2:3], 0, s[12:13]
	s_mov_b32 m0, s44
	s_add_u32 s4, s2, 0x40080
	global_load_lds_dwordx4 v[2:3], off
	v_lshl_add_u64 v[2:3], v[4:5], 0, s[12:13]
	s_mov_b32 m0, s45
	s_addc_u32 s5, s3, 0
	global_load_lds_dwordx4 v[2:3], off
	s_add_i32 m0, s29, 0x1c000
	v_lshl_add_u64 v[2:3], s[4:5], 0, v[182:183]
	global_load_lds_dwordx4 v[2:3], off
	v_lshl_add_u64 v[2:3], s[4:5], 0, v[186:187]
	s_add_i32 m0, s29, 0x1e000
	v_lshlrev_b32_e32 v4, 2, v179
	global_load_lds_dwordx4 v[2:3], off
	v_lshlrev_b32_e32 v2, 1, v178
	v_lshl_or_b32 v3, v179, 6, v2
	v_and_b32_e32 v4, 32, v4
	v_lshl_or_b32 v217, s1, 6, v179
	v_bitop3_b32 v3, v3, s7, v4 bitop3:0xde
	v_lshlrev_b32_e32 v4, 6, v0
	s_movk_i32 s1, 0x3c0
	v_and_or_b32 v2, v4, s1, v2
	v_and_b32_e32 v4, 32, v214
	v_bitop3_b32 v218, s14, v2, v4 bitop3:0xf6
	v_lshlrev_b32_e32 v2, 8, v0
	v_and_b32_e32 v2, 0x18000, v2
	v_lshlrev_b32_e32 v4, 11, v12
	v_or3_b32 v2, v10, v2, v4
	v_add_u32_e32 v190, v2, v11
	v_lshlrev_b32_e32 v2, 4, v13
	v_and_b32_e32 v2, 0x38000, v2
	s_waitcnt vmcnt(8)
	s_barrier
	s_waitcnt vmcnt(6)
	s_cmpk_lt_u32 s0, 0x100
	v_or3_b32 v2, v10, v2, v4
	s_cselect_b64 s[14:15], -1, 0
	v_add_u32_e32 v192, v2, v11
	s_add_i32 s48, 0, 0x10000
	s_add_i32 s49, 0, 0x14000
	v_mbcnt_lo_u32_b32 v2, -1, 0
	s_ashr_i32 s46, s75, 31
	s_ashr_i32 s47, s64, 31
	v_mov_b32_e32 v191, v189
	v_mov_b32_e32 v193, v189
	v_mov_b64_e32 v[194:195], 0x300
	v_mov_b64_e32 v[196:197], 0x2ff
	v_add_u32_e32 v219, s48, v218
	v_add_u32_e32 v220, s49, v218
	v_add_u32_e32 v221, 0, v3
	s_mov_b32 s18, 0x3e38aa3b
	v_mov_b32_e32 v222, 0x358637bd
	v_mbcnt_hi_u32_b32 v223, -1, v2
	s_barrier
	s_branch .LBB0_672

.LBB0_910:
	s_mov_b64 s[14:15], 0x80
	s_and_b32 s6, s4, 3
	s_add_i32 m0, s27, 0x18000
	v_lshl_add_u64 v[8:9], v[8:9], 0, s[14:15]
	s_lshl_b32 s7, s1, 13
	s_lshl_b32 s11, s6, 12
	global_load_lds_dwordx4 v[8:9], off
	v_lshl_add_u64 v[4:5], v[4:5], 0, s[14:15]
	s_add_i32 m0, s27, 0x1a000
	s_add_i32 s42, s27, 0x8000
	s_add_i32 s43, s27, 0xa000
	global_load_lds_dwordx4 v[4:5], off
	v_lshl_add_u64 v[2:3], v[2:3], 0, s[14:15]
	s_mov_b32 m0, s42
	s_add_u32 s4, s2, 0x40080
	global_load_lds_dwordx4 v[2:3], off
	v_lshl_add_u64 v[2:3], v[6:7], 0, s[14:15]
	s_mov_b32 m0, s43
	s_addc_u32 s5, s3, 0
	global_load_lds_dwordx4 v[2:3], off
	s_add_i32 m0, s27, 0x1c000
	v_lshl_add_u64 v[2:3], s[4:5], 0, v[156:157]
	global_load_lds_dwordx4 v[2:3], off
	v_lshl_add_u64 v[2:3], s[4:5], 0, v[160:161]
	s_add_i32 m0, s27, 0x1e000
	s_cmpk_lt_u32 s0, 0x100
	global_load_lds_dwordx4 v[2:3], off
	v_bfe_u32 v2, v0, 4, 2
	v_and_b32_e32 v3, 15, v0
	v_lshl_or_b32 v182, s1, 6, v3
	v_lshlrev_b32_e32 v4, 3, v2
	v_lshlrev_b32_e32 v5, 4, v2
	v_cmp_eq_u32_e64 s[4:5], 0, v2
	v_lshlrev_b32_e32 v2, 8, v0
	v_lshlrev_b32_e32 v6, 2, v182
	v_lshl_or_b32 v184, s6, 5, v4
	v_and_b32_e32 v2, 0x18000, v2
	v_lshlrev_b32_e32 v4, 11, v12
	v_lshl_or_b32 v3, v3, 6, v5
	v_and_b32_e32 v7, 32, v6
	v_or3_b32 v2, v10, v2, v4
	v_bitop3_b32 v3, v3, s7, v7 bitop3:0xde
	v_lshlrev_b32_e32 v7, 6, v0
	s_movk_i32 s1, 0x3c0
	v_add_u32_e32 v162, v2, v11
	v_lshlrev_b32_e32 v2, 4, v13
	v_and_or_b32 v5, v7, s1, v5
	v_lshlrev_b32_e32 v7, 2, v0
	v_and_b32_e32 v2, 0x38000, v2
	v_and_b32_e32 v8, 32, v7
	s_waitcnt vmcnt(8)
	s_barrier
	s_waitcnt vmcnt(6)
	s_cselect_b64 s[16:17], -1, 0
	s_lshl_b32 s0, s6, 10
	s_add_i32 s1, 0, 0x20000
	v_or3_b32 v2, v10, v2, v4
	v_bitop3_b32 v183, s11, v5, v8 bitop3:0xf6
	s_add_i32 s0, s1, s0
	v_add_u32_e32 v164, v2, v11
	s_add_i32 s46, 0, 0x10000
	s_add_i32 s47, 0, 0x14000
	v_mbcnt_lo_u32_b32 v2, -1, 0
	s_ashr_i32 s44, s75, 31
	s_ashr_i32 s45, s64, 31
	v_add_u32_e32 v185, s0, v6
	v_add_u32_e32 v186, s1, v7
	v_mov_b32_e32 v163, v157
	v_mov_b32_e32 v165, v157
	v_mov_b64_e32 v[166:167], 0x100
	v_mov_b64_e32 v[168:169], 0xff
	v_add_u32_e32 v187, s46, v183
	v_add_u32_e32 v188, s47, v183
	v_add_u32_e32 v189, 0, v3
	v_mbcnt_hi_u32_b32 v190, -1, v2
	s_barrier
	s_branch .LBB0_913

.LBB0_1003:
	s_add_u32 s12, s72, 0x9400000
	s_addc_u32 s13, s73, 0
	s_lshl_b32 s5, s5, 5
	s_mov_b64 s[14:15], 0x80
	s_and_b32 s5, s5, 0x60
	s_add_i32 m0, s27, 0x18000
	v_lshl_add_u64 v[10:11], v[10:11], 0, s[14:15]
	s_lshl_b32 s8, s1, 13
	s_lshl_b32 s18, s5, 7
	global_load_lds_dwordx4 v[10:11], off
	v_lshl_add_u64 v[8:9], v[8:9], 0, s[14:15]
	s_add_i32 m0, s27, 0x1a000
	s_add_i32 s41, s27, 0x8000
	s_add_i32 s42, s27, 0xa000
	global_load_lds_dwordx4 v[8:9], off
	v_lshl_add_u64 v[4:5], v[4:5], 0, s[14:15]
	s_mov_b32 m0, s41
	s_add_u32 s16, s2, 0x40080
	global_load_lds_dwordx4 v[4:5], off
	v_lshl_add_u64 v[4:5], v[6:7], 0, s[14:15]
	s_mov_b32 m0, s42
	s_addc_u32 s17, s3, 0
	global_load_lds_dwordx4 v[4:5], off
	s_add_i32 m0, s27, 0x1c000
	v_lshl_add_u64 v[4:5], s[16:17], 0, v[134:135]
	global_load_lds_dwordx4 v[4:5], off
	v_lshl_add_u64 v[4:5], s[16:17], 0, v[130:131]
	s_add_i32 m0, s27, 0x1e000
	v_lshlrev_b32_e32 v7, 6, v0
	global_load_lds_dwordx4 v[4:5], off
	v_and_b32_e32 v4, 15, v0
	v_lshl_or_b32 v165, s1, 6, v4
	v_lshlrev_b32_e32 v5, 1, v2
	s_movk_i32 s1, 0x3c0
	v_lshl_or_b32 v4, v4, 6, v5
	v_and_b32_e32 v6, 32, v164
	v_and_or_b32 v5, v7, s1, v5
	v_bitop3_b32 v166, s18, v5, v6 bitop3:0xf6
	v_lshlrev_b32_e32 v5, 8, v0
	v_lshlrev_b32_e32 v3, 4, v3
	v_bitop3_b32 v4, v4, s8, v6 bitop3:0xde
	s_waitcnt vmcnt(8)
	s_barrier
	s_waitcnt vmcnt(6)
	s_cmpk_lt_u32 s0, 0x100
	v_and_b32_e32 v5, 0x18000, v5
	v_lshlrev_b32_e32 v6, 11, v14
	v_and_b32_e32 v3, 0x38000, v3
	s_cselect_b64 s[16:17], -1, 0
	v_or3_b32 v5, v12, v5, v6
	v_or3_b32 v3, v12, v3, v6
	s_add_i32 s44, 0, 0x10000
	s_add_i32 s45, 0, 0x14000
	s_sext_i32_i8 s48, s4
	s_ashr_i32 s43, s75, 31
	v_add_u32_e32 v140, v5, v13
	v_mov_b32_e32 v141, v139
	v_add_u32_e32 v142, v3, v13
	v_mov_b32_e32 v143, v139
	v_mov_b64_e32 v[144:145], 0x580
	v_mov_b64_e32 v[146:147], 0x57f
	v_add_u32_e32 v167, s44, v166
	v_add_u32_e32 v168, s45, v166
	v_add_u32_e32 v169, 0, v4
	v_mov_b32_e32 v170, 0x358637bd
	s_movk_i32 s46, 0x1600
	s_lshl_b32 s8, s5, 1
	v_lshlrev_b32_e32 v138, 1, v2
	s_mov_b32 s47, s9
	s_barrier
	s_branch .LBB0_1006

.LBB0_1109:
	s_mov_b64 s[16:17], 0x80
	s_and_b32 s6, s4, 3
	s_add_i32 m0, s34, 0x18000
	v_lshl_add_u64 v[8:9], v[8:9], 0, s[16:17]
	s_lshl_b32 s7, s1, 13
	s_lshl_b32 s8, s6, 12
	global_load_lds_dwordx4 v[8:9], off
	v_lshl_add_u64 v[6:7], v[6:7], 0, s[16:17]
	s_add_i32 m0, s34, 0x1a000
	s_add_i32 s39, s34, 0x8000
	s_add_i32 s40, s34, 0xa000
	global_load_lds_dwordx4 v[6:7], off
	v_lshl_add_u64 v[2:3], v[2:3], 0, s[16:17]
	s_mov_b32 m0, s39
	s_add_u32 s4, s2, 0xb0080
	global_load_lds_dwordx4 v[2:3], off
	v_lshl_add_u64 v[2:3], v[4:5], 0, s[16:17]
	s_mov_b32 m0, s40
	s_addc_u32 s5, s3, 0
	global_load_lds_dwordx4 v[2:3], off
	s_add_i32 m0, s34, 0x1c000
	v_lshl_add_u64 v[2:3], s[4:5], 0, v[156:157]
	global_load_lds_dwordx4 v[2:3], off
	v_lshl_add_u64 v[2:3], s[4:5], 0, v[160:161]
	s_add_i32 m0, s34, 0x1e000
	s_cmpk_lt_u32 s0, 0x100
	global_load_lds_dwordx4 v[2:3], off
	v_and_b32_e32 v3, 15, v0
	v_bfe_u32 v2, v0, 4, 2
	v_lshl_or_b32 v182, s1, 6, v3
	v_lshlrev_b32_e32 v5, 4, v2
	v_lshlrev_b32_e32 v6, 2, v182
	v_lshl_or_b32 v3, v3, 6, v5
	v_and_b32_e32 v7, 32, v6
	v_bitop3_b32 v3, v3, s7, v7 bitop3:0xde
	v_lshlrev_b32_e32 v7, 6, v0
	s_movk_i32 s1, 0x3c0
	v_lshlrev_b32_e32 v4, 3, v2
	v_and_or_b32 v5, v7, s1, v5
	v_lshlrev_b32_e32 v7, 2, v0
	v_cmp_eq_u32_e64 s[4:5], 0, v2
	v_add_u16_e32 v2, v10, v11
	v_and_b32_e32 v8, 32, v7
	s_waitcnt vmcnt(8)
	s_barrier
	s_waitcnt vmcnt(6)
	s_cselect_b64 s[18:19], -1, 0
	s_lshl_b32 s0, s6, 10
	s_add_i32 s1, 0, 0x20000
	v_lshrrev_b16_e32 v2, 1, v2
	v_bitop3_b32 v183, s8, v5, v8 bitop3:0xf6
	s_add_i32 s0, s1, s0
	v_add_lshl_u32 v162, v12, v2, 1
	v_add_lshl_u32 v164, v13, v2, 1
	s_add_i32 s43, 0, 0x10000
	s_add_i32 s44, 0, 0x14000
	v_mbcnt_lo_u32_b32 v2, -1, 0
	v_lshl_or_b32 v184, s6, 5, v4
	s_ashr_i32 s41, s75, 31
	s_ashr_i32 s42, s64, 31
	v_add_u32_e32 v185, s0, v6
	v_add_u32_e32 v186, s1, v7
	v_mov_b32_e32 v163, v157
	v_mov_b32_e32 v165, v157
	v_mov_b64_e32 v[166:167], 0x100
	v_mov_b64_e32 v[168:169], 0xff
	v_add_u32_e32 v187, s43, v183
	v_add_u32_e32 v188, s44, v183
	v_add_u32_e32 v189, 0, v3
	v_mbcnt_hi_u32_b32 v190, -1, v2
	s_mov_b64 s[20:21], 0x58000
	s_barrier
	s_branch .LBB0_1112

.LBB0_1208:
	s_add_u32 s14, s72, 0x9400000
	s_addc_u32 s15, s73, 0
	s_add_u32 s16, s72, 0xd400000
	s_addc_u32 s17, s73, 0
	s_add_u32 s20, s72, 0x15400000
	s_addc_u32 s21, s73, 0
	s_lshl_b32 s4, s4, 5
	s_mov_b64 s[22:23], 0x80
	s_and_b32 s48, s4, 0x60
	s_add_i32 m0, s43, 0x18000
	v_lshl_add_u64 v[8:9], v[8:9], 0, s[22:23]
	s_lshl_b32 s47, s1, 6
	s_lshl_b32 s1, s1, 13
	s_lshl_b32 s7, s48, 7
	global_load_lds_dwordx4 v[8:9], off
	v_lshl_add_u64 v[6:7], v[6:7], 0, s[22:23]
	s_add_i32 m0, s43, 0x1a000
	s_add_i32 s49, s43, 0x8000
	s_add_i32 s50, s43, 0xa000
	global_load_lds_dwordx4 v[6:7], off
	v_lshl_add_u64 v[2:3], v[2:3], 0, s[22:23]
	s_mov_b32 m0, s49
	s_add_u32 s4, s2, 0x40080
	global_load_lds_dwordx4 v[2:3], off
	v_lshl_add_u64 v[2:3], v[4:5], 0, s[22:23]
	s_mov_b32 m0, s50
	s_addc_u32 s5, s3, 0
	global_load_lds_dwordx4 v[2:3], off
	s_add_i32 m0, s43, 0x1c000
	v_lshl_add_u64 v[2:3], s[4:5], 0, v[162:163]
	global_load_lds_dwordx4 v[2:3], off
	v_lshl_add_u64 v[2:3], s[4:5], 0, v[166:167]
	s_add_i32 m0, s43, 0x1e000
	v_lshlrev_b32_e32 v4, 2, v159
	global_load_lds_dwordx4 v[2:3], off
	v_lshlrev_b32_e32 v2, 1, v158
	v_lshl_or_b32 v3, v159, 6, v2
	v_and_b32_e32 v4, 32, v4
	v_bitop3_b32 v3, v3, s1, v4 bitop3:0xde
	v_lshlrev_b32_e32 v4, 6, v0
	s_movk_i32 s1, 0x3c0
	v_and_or_b32 v2, v4, s1, v2
	v_and_b32_e32 v4, 32, v205
	v_bitop3_b32 v206, s7, v2, v4 bitop3:0xf6
	v_or_b32_e32 v2, s48, v158
	v_or_b32_e32 v207, 0xfffff800, v2
	v_lshlrev_b32_e32 v2, 8, v0
	v_and_b32_e32 v2, 0x18000, v2
	v_lshlrev_b32_e32 v4, 11, v12
	v_or3_b32 v2, v10, v2, v4
	v_add_u32_e32 v170, v2, v11
	v_lshlrev_b32_e32 v2, 4, v13
	s_waitcnt vmcnt(8)
	s_barrier
	s_waitcnt vmcnt(6)
	s_cmpk_lt_u32 s0, 0x100
	v_and_b32_e32 v2, 0x38000, v2
	s_cselect_b64 s[24:25], -1, 0
	v_or3_b32 v2, v10, v2, v4
	s_add_i32 s53, 0, 0x10000
	s_add_i32 s54, 0, 0x14000
	s_ashr_i32 s51, s75, 31
	s_ashr_i32 s52, s64, 31
	v_mov_b32_e32 v171, v169
	v_add_u32_e32 v172, v2, v11
	v_mov_b32_e32 v173, v169
	v_mov_b64_e32 v[174:175], 0x600
	v_mov_b64_e32 v[176:177], 0x5ff
	v_add_u32_e32 v208, s53, v206
	v_add_u32_e32 v209, s54, v206
	v_add_u32_e32 v210, 0, v3
	v_mov_b32_e32 v211, 0x358637bd
	s_mov_b32 s26, 0xbfb8aa3b
	s_movk_i32 s55, 0x7c
	s_mov_b32 s56, 0
	s_barrier
	s_branch .LBB0_1211

.LBB0_1616:
	s_mov_b64 s[14:15], 0x80
	s_and_b32 s6, s4, 3
	s_add_i32 m0, s37, 0x18000
	v_lshl_add_u64 v[8:9], v[8:9], 0, s[14:15]
	s_lshl_b32 s7, s1, 13
	s_lshl_b32 s11, s6, 12
	global_load_lds_dwordx4 v[8:9], off
	v_lshl_add_u64 v[6:7], v[6:7], 0, s[14:15]
	s_add_i32 m0, s37, 0x1a000
	s_add_i32 s50, s37, 0x8000
	s_add_i32 s51, s37, 0xa000
	global_load_lds_dwordx4 v[6:7], off
	v_lshl_add_u64 v[2:3], v[2:3], 0, s[14:15]
	s_mov_b32 m0, s50
	s_add_u32 s4, s2, 0x80080
	global_load_lds_dwordx4 v[2:3], off
	v_lshl_add_u64 v[2:3], v[4:5], 0, s[14:15]
	s_mov_b32 m0, s51
	s_addc_u32 s5, s3, 0
	global_load_lds_dwordx4 v[2:3], off
	s_add_i32 m0, s37, 0x1c000
	v_lshl_add_u64 v[2:3], s[4:5], 0, v[156:157]
	global_load_lds_dwordx4 v[2:3], off
	v_lshl_add_u64 v[2:3], s[4:5], 0, v[160:161]
	s_add_i32 m0, s37, 0x1e000
	s_cmpk_lt_u32 s0, 0x100
	global_load_lds_dwordx4 v[2:3], off
	v_bfe_u32 v2, v0, 4, 2
	v_and_b32_e32 v3, 15, v0
	v_lshl_or_b32 v1, s1, 6, v3
	v_lshlrev_b32_e32 v4, 3, v2
	v_lshlrev_b32_e32 v5, 4, v2
	v_cmp_eq_u32_e64 s[4:5], 0, v2
	v_lshlrev_b32_e32 v2, 9, v0
	v_lshlrev_b32_e32 v6, 2, v1
	v_lshl_or_b32 v183, s6, 5, v4
	v_and_b32_e32 v2, 0x30000, v2
	v_lshlrev_b32_e32 v4, 12, v12
	v_lshl_or_b32 v3, v3, 6, v5
	v_and_b32_e32 v7, 32, v6
	v_or3_b32 v2, v10, v2, v4
	v_bitop3_b32 v3, v3, s7, v7 bitop3:0xde
	v_lshlrev_b32_e32 v7, 6, v0
	s_movk_i32 s1, 0x3c0
	v_add_u32_e32 v162, v2, v11
	v_lshlrev_b32_e32 v2, 5, v13
	v_and_or_b32 v5, v7, s1, v5
	v_lshlrev_b32_e32 v7, 2, v0
	v_and_b32_e32 v2, 0x70000, v2
	v_and_b32_e32 v8, 32, v7
	s_waitcnt vmcnt(8)
	s_barrier
	s_waitcnt vmcnt(6)
	s_cselect_b64 s[16:17], -1, 0
	s_lshl_b32 s0, s6, 10
	s_add_i32 s1, 0, 0x20000
	v_or3_b32 v2, v10, v2, v4
	v_bitop3_b32 v182, s11, v5, v8 bitop3:0xf6
	s_add_i32 s0, s1, s0
	v_add_u32_e32 v164, v2, v11
	s_add_i32 s54, 0, 0x10000
	s_add_i32 s55, 0, 0x14000
	v_mbcnt_lo_u32_b32 v2, -1, 0
	s_ashr_i32 s52, s75, 31
	s_ashr_i32 s53, s64, 31
	v_add_u32_e32 v184, s0, v6
	v_add_u32_e32 v185, s1, v7
	v_mov_b32_e32 v163, v157
	v_mov_b32_e32 v165, v157
	v_mov_b64_e32 v[166:167], 0x100
	v_mov_b64_e32 v[168:169], 0xff
	v_add_u32_e32 v186, s54, v182
	v_add_u32_e32 v187, s55, v182
	v_add_u32_e32 v188, 0, v3
	v_mbcnt_hi_u32_b32 v189, -1, v2
	s_mov_b64 s[18:19], 0x40000
	s_mov_b64 s[20:21], 0x48000
	s_mov_b64 s[22:23], 0x50000
	s_mov_b64 s[24:25], 0x58000
	s_barrier
	s_branch .LBB0_1619

.LBB0_1709:
	s_add_u32 s12, s72, 0x9400000
	s_addc_u32 s13, s73, 0
	s_lshl_b32 s5, s5, 5
	s_mov_b64 s[14:15], 0x80
	s_and_b32 s5, s5, 0x60
	s_add_i32 m0, s27, 0x18000
	v_lshl_add_u64 v[10:11], v[10:11], 0, s[14:15]
	s_lshl_b32 s8, s1, 13
	s_lshl_b32 s18, s5, 7
	global_load_lds_dwordx4 v[10:11], off
	v_lshl_add_u64 v[8:9], v[8:9], 0, s[14:15]
	s_add_i32 m0, s27, 0x1a000
	s_add_i32 s41, s27, 0x8000
	s_add_i32 s42, s27, 0xa000
	global_load_lds_dwordx4 v[8:9], off
	v_lshl_add_u64 v[4:5], v[4:5], 0, s[14:15]
	s_mov_b32 m0, s41
	s_add_u32 s16, s2, 0x40080
	global_load_lds_dwordx4 v[4:5], off
	v_lshl_add_u64 v[4:5], v[6:7], 0, s[14:15]
	s_mov_b32 m0, s42
	s_addc_u32 s17, s3, 0
	global_load_lds_dwordx4 v[4:5], off
	s_add_i32 m0, s27, 0x1c000
	v_lshl_add_u64 v[4:5], s[16:17], 0, v[134:135]
	global_load_lds_dwordx4 v[4:5], off
	v_lshl_add_u64 v[4:5], s[16:17], 0, v[130:131]
	s_add_i32 m0, s27, 0x1e000
	v_lshlrev_b32_e32 v7, 6, v0
	global_load_lds_dwordx4 v[4:5], off
	v_and_b32_e32 v4, 15, v0
	v_lshl_or_b32 v164, s1, 6, v4
	v_lshlrev_b32_e32 v5, 1, v2
	s_movk_i32 s1, 0x3c0
	v_lshl_or_b32 v4, v4, 6, v5
	v_and_b32_e32 v6, 32, v1
	v_and_or_b32 v5, v7, s1, v5
	v_bitop3_b32 v165, s18, v5, v6 bitop3:0xf6
	v_lshlrev_b32_e32 v5, 8, v0
	v_lshlrev_b32_e32 v3, 4, v3
	v_bitop3_b32 v4, v4, s8, v6 bitop3:0xde
	s_waitcnt vmcnt(8)
	s_barrier
	s_waitcnt vmcnt(6)
	s_cmpk_lt_u32 s0, 0x100
	v_and_b32_e32 v5, 0x18000, v5
	v_lshlrev_b32_e32 v6, 11, v14
	v_and_b32_e32 v3, 0x38000, v3
	s_cselect_b64 s[16:17], -1, 0
	v_or3_b32 v5, v12, v5, v6
	v_or3_b32 v3, v12, v3, v6
	s_add_i32 s44, 0, 0x10000
	s_add_i32 s45, 0, 0x14000
	s_sext_i32_i8 s48, s4
	s_ashr_i32 s43, s75, 31
	v_add_u32_e32 v140, v5, v13
	v_mov_b32_e32 v141, v139
	v_add_u32_e32 v142, v3, v13
	v_mov_b32_e32 v143, v139
	v_mov_b64_e32 v[144:145], 0x580
	v_mov_b64_e32 v[146:147], 0x57f
	v_add_u32_e32 v166, s44, v165
	v_add_u32_e32 v167, s45, v165
	v_add_u32_e32 v168, 0, v4
	v_mov_b32_e32 v169, 0x358637bd
	s_movk_i32 s46, 0x1600
	s_lshl_b32 s8, s5, 1
	v_lshlrev_b32_e32 v138, 1, v2
	s_mov_b32 s47, s9
	s_barrier
	s_branch .LBB0_1712

.LBB0_1827:
	s_mov_b64 s[16:17], 0x80
	s_and_b32 s6, s4, 3
	s_add_i32 m0, s40, 0x18000
	v_lshl_add_u64 v[8:9], v[8:9], 0, s[16:17]
	s_lshl_b32 s7, s1, 13
	s_lshl_b32 s8, s6, 12
	global_load_lds_dwordx4 v[8:9], off
	v_lshl_add_u64 v[6:7], v[6:7], 0, s[16:17]
	s_add_i32 m0, s40, 0x1a000
	s_add_i32 s45, s40, 0x8000
	s_add_i32 s46, s40, 0xa000
	global_load_lds_dwordx4 v[6:7], off
	v_lshl_add_u64 v[2:3], v[2:3], 0, s[16:17]
	s_mov_b32 m0, s45
	s_add_u32 s4, s2, 0xb0080
	global_load_lds_dwordx4 v[2:3], off
	v_lshl_add_u64 v[2:3], v[4:5], 0, s[16:17]
	s_mov_b32 m0, s46
	s_addc_u32 s5, s3, 0
	global_load_lds_dwordx4 v[2:3], off
	s_add_i32 m0, s40, 0x1c000
	v_lshl_add_u64 v[2:3], s[4:5], 0, v[156:157]
	global_load_lds_dwordx4 v[2:3], off
	v_lshl_add_u64 v[2:3], s[4:5], 0, v[160:161]
	s_add_i32 m0, s40, 0x1e000
	s_cmpk_lt_u32 s0, 0x100
	global_load_lds_dwordx4 v[2:3], off
	v_and_b32_e32 v3, 15, v0
	v_bfe_u32 v2, v0, 4, 2
	v_lshl_or_b32 v1, s1, 6, v3
	v_lshlrev_b32_e32 v5, 4, v2
	v_lshlrev_b32_e32 v6, 2, v1
	v_lshl_or_b32 v3, v3, 6, v5
	v_and_b32_e32 v7, 32, v6
	v_bitop3_b32 v3, v3, s7, v7 bitop3:0xde
	v_lshlrev_b32_e32 v7, 6, v0
	s_movk_i32 s1, 0x3c0
	v_lshlrev_b32_e32 v4, 3, v2
	v_and_or_b32 v5, v7, s1, v5
	v_lshlrev_b32_e32 v7, 2, v0
	v_cmp_eq_u32_e64 s[4:5], 0, v2
	v_add_u16_e32 v2, v10, v11
	v_and_b32_e32 v8, 32, v7
	s_waitcnt vmcnt(8)
	s_barrier
	s_waitcnt vmcnt(6)
	s_cselect_b64 s[18:19], -1, 0
	s_lshl_b32 s0, s6, 10
	s_add_i32 s1, 0, 0x20000
	v_lshrrev_b16_e32 v2, 1, v2
	v_bitop3_b32 v182, s8, v5, v8 bitop3:0xf6
	s_add_i32 s0, s1, s0
	v_add_lshl_u32 v162, v12, v2, 1
	v_add_lshl_u32 v164, v13, v2, 1
	s_add_i32 s49, 0, 0x10000
	s_add_i32 s50, 0, 0x14000
	v_mbcnt_lo_u32_b32 v2, -1, 0
	v_lshl_or_b32 v183, s6, 5, v4
	s_ashr_i32 s47, s75, 31
	s_ashr_i32 s48, s64, 31
	v_add_u32_e32 v184, s0, v6
	v_add_u32_e32 v185, s1, v7
	v_mov_b32_e32 v163, v157
	v_mov_b32_e32 v165, v157
	v_mov_b64_e32 v[166:167], 0x100
	v_mov_b64_e32 v[168:169], 0xff
	v_add_u32_e32 v186, s49, v182
	v_add_u32_e32 v187, s50, v182
	v_add_u32_e32 v188, 0, v3
	v_mbcnt_hi_u32_b32 v189, -1, v2
	s_mov_b64 s[20:21], 0x40000
	s_mov_b64 s[22:23], 0x48000
	s_mov_b64 s[24:25], 0x50000
	s_mov_b64 s[26:27], 0x58000
	s_barrier
	s_branch .LBB0_1830

.LBB0_1928:
	s_add_u32 s12, s72, 0x9400000
	s_addc_u32 s13, s73, 0
	s_lshl_b32 s5, s5, 5
	s_mov_b64 s[14:15], 0x80
	s_and_b32 s5, s5, 0x60
	s_add_i32 m0, s27, 0x18000
	v_lshl_add_u64 v[10:11], v[10:11], 0, s[14:15]
	s_lshl_b32 s8, s1, 13
	s_lshl_b32 s18, s5, 7
	global_load_lds_dwordx4 v[10:11], off
	v_lshl_add_u64 v[8:9], v[8:9], 0, s[14:15]
	s_add_i32 m0, s27, 0x1a000
	s_add_i32 s40, s27, 0x8000
	s_add_i32 s41, s27, 0xa000
	global_load_lds_dwordx4 v[8:9], off
	v_lshl_add_u64 v[4:5], v[4:5], 0, s[14:15]
	s_mov_b32 m0, s40
	s_add_u32 s16, s2, 0x40080
	global_load_lds_dwordx4 v[4:5], off
	v_lshl_add_u64 v[4:5], v[6:7], 0, s[14:15]
	s_mov_b32 m0, s41
	s_addc_u32 s17, s3, 0
	global_load_lds_dwordx4 v[4:5], off
	s_add_i32 m0, s27, 0x1c000
	v_lshl_add_u64 v[4:5], s[16:17], 0, v[132:133]
	global_load_lds_dwordx4 v[4:5], off
	v_lshl_add_u64 v[4:5], s[16:17], 0, v[136:137]
	s_add_i32 m0, s27, 0x1e000
	v_lshlrev_b32_e32 v6, 2, v0
	global_load_lds_dwordx4 v[4:5], off
	v_and_b32_e32 v4, 15, v0
	v_lshl_or_b32 v1, s1, 6, v4
	v_lshlrev_b32_e32 v5, 1, v2
	v_lshlrev_b32_e32 v7, 6, v0
	s_movk_i32 s1, 0x3c0
	v_lshl_or_b32 v4, v4, 6, v5
	v_and_b32_e32 v6, 32, v6
	v_and_or_b32 v5, v7, s1, v5
	v_bitop3_b32 v160, s18, v5, v6 bitop3:0xf6
	v_lshlrev_b32_e32 v5, 8, v0
	v_bitop3_b32 v4, v4, s8, v6 bitop3:0xde
	v_and_b32_e32 v5, 0x18000, v5
	v_lshlrev_b32_e32 v6, 11, v13
	v_or3_b32 v5, v3, v5, v6
	v_add_u32_e32 v140, v5, v12
	v_lshlrev_b32_e32 v5, 4, v14
	s_waitcnt vmcnt(8)
	s_barrier
	s_waitcnt vmcnt(6)
	s_cmpk_lt_u32 s0, 0x100
	v_and_b32_e32 v5, 0x38000, v5
	s_cselect_b64 s[16:17], -1, 0
	v_or3_b32 v3, v3, v5, v6
	s_add_i32 s43, 0, 0x10000
	s_add_i32 s44, 0, 0x14000
	s_sext_i32_i8 s46, s4
	s_ashr_i32 s42, s75, 31
	v_mov_b32_e32 v141, v139
	v_add_u32_e32 v142, v3, v12
	v_mov_b32_e32 v143, v139
	v_mov_b64_e32 v[144:145], 0x200
	v_mov_b64_e32 v[146:147], 0x1ff
	v_add_u32_e32 v161, s43, v160
	v_add_u32_e32 v162, s44, v160
	v_add_u32_e32 v163, 0, v4
	v_mov_b32_e32 v164, 0x358637bd
	s_lshl_b32 s8, s5, 1
	v_lshlrev_b32_e32 v138, 1, v2
	s_mov_b32 s45, s9
	s_barrier
	s_branch .LBB0_1931

.LBB0_2009:
	s_add_u32 s18, s72, 0x9400000
	s_addc_u32 s19, s73, 0
	v_readlane_b32 s36, v254, 18
	s_add_u32 s20, s72, 0xb400000
	v_readlane_b32 s48, v254, 30
	v_readlane_b32 s49, v254, 31
	s_addc_u32 s21, s73, 0
	s_mov_b64 s[12:13], s[48:49]
	s_add_u32 s22, s12, 0x3000
	s_addc_u32 s23, s13, 0
	s_lshl_b32 s4, s4, 5
	s_mov_b64 s[24:25], 0x80
	s_and_b32 s9, s4, 0x60
	s_add_i32 m0, s66, 0x18000
	v_lshl_add_u64 v[8:9], v[8:9], 0, s[24:25]
	s_mov_b64 s[80:81], s[72:73]
	s_lshl_b32 s7, s1, 13
	s_lshl_b32 s12, s9, 7
	global_load_lds_dwordx4 v[8:9], off
	v_lshl_add_u64 v[6:7], v[6:7], 0, s[24:25]
	s_add_i32 m0, s66, 0x1a000
	s_add_i32 s71, s66, 0x8000
	s_add_i32 s72, s66, 0xa000
	global_load_lds_dwordx4 v[6:7], off
	v_lshl_add_u64 v[2:3], v[2:3], 0, s[24:25]
	s_mov_b32 m0, s71
	s_add_u32 s4, s2, 0x40080
	global_load_lds_dwordx4 v[2:3], off
	v_lshl_add_u64 v[2:3], v[4:5], 0, s[24:25]
	s_mov_b32 m0, s72
	s_addc_u32 s5, s3, 0
	global_load_lds_dwordx4 v[2:3], off
	s_add_i32 m0, s66, 0x1c000
	v_lshl_add_u64 v[2:3], s[4:5], 0, v[172:173]
	global_load_lds_dwordx4 v[2:3], off
	v_lshl_add_u64 v[2:3], s[4:5], 0, v[176:177]
	s_add_i32 m0, s66, 0x1e000
	v_lshlrev_b32_e32 v4, 2, v0
	global_load_lds_dwordx4 v[2:3], off
	v_and_b32_e32 v2, 15, v0
	v_lshl_or_b32 v1, s1, 6, v2
	v_lshlrev_b32_e32 v3, 1, v14
	v_lshlrev_b32_e32 v6, 6, v0
	s_movk_i32 s1, 0x3c0
	v_lshl_or_b32 v2, v2, 6, v3
	v_and_b32_e32 v5, 32, v4
	v_and_or_b32 v3, v6, s1, v3
	s_cmpk_lt_u32 s0, 0x100
	v_bitop3_b32 v222, s12, v3, v5 bitop3:0xf6
	s_cselect_b64 s[26:27], -1, 0
	s_add_i32 s0, 0, 0x20000
	v_lshlrev_b32_e32 v3, 8, v0
	v_add_u32_e32 v224, s0, v4
	v_and_b32_e32 v3, 0x18000, v3
	v_lshlrev_b32_e32 v4, 11, v12
	v_or3_b32 v3, v10, v3, v4
	v_add_u32_e32 v180, v3, v11
	v_lshlrev_b32_e32 v3, 4, v13
	s_waitcnt vmcnt(8)
	s_barrier
	s_waitcnt vmcnt(6)
	v_or_b32_e32 v178, s9, v14
	v_and_b32_e32 v3, 0x38000, v3
	v_readlane_b32 s37, v254, 19
	v_readlane_b32 s38, v254, 20
	v_readlane_b32 s39, v254, 21
	v_readlane_b32 s40, v254, 22
	v_readlane_b32 s41, v254, 23
	v_readlane_b32 s42, v254, 24
	v_readlane_b32 s43, v254, 25
	v_readlane_b32 s44, v254, 26
	v_readlane_b32 s45, v254, 27
	v_readlane_b32 s46, v254, 28
	v_readlane_b32 s47, v254, 29
	v_readlane_b32 s50, v254, 32
	v_readlane_b32 s51, v254, 33
	v_bitop3_b32 v2, v2, s7, v5 bitop3:0xde
	v_or_b32_e32 v223, 0x80, v178
	s_ashr_i32 s73, s75, 31
	v_or3_b32 v3, v10, v3, v4
	s_add_i32 s75, 0, 0x10000
	s_add_i32 s76, 0, 0x14000
	s_ashr_i32 s74, s96, 31
	v_lshl_add_u32 v225, v178, 2, s0
	v_lshl_add_u32 v226, v223, 2, s0
	v_mov_b32_e32 v179, v173
	v_mov_b32_e32 v181, v173
	v_add_u32_e32 v182, v3, v11
	v_mov_b32_e32 v183, v173
	v_mov_b64_e32 v[184:185], 0x100
	v_mov_b64_e32 v[186:187], 0xff
	v_add_u32_e32 v227, s75, v222
	v_add_u32_e32 v228, s76, v222
	v_add_u32_e32 v229, 0, v2
	v_mov_b32_e32 v230, 0x358637bd
	s_mov_b64 s[28:29], 0x7000
	s_mov_b64 s[30:31], 0x7800
	s_mov_b64 s[34:35], 0xf000
	s_mov_b64 s[36:37], 0xf800
	s_mov_b64 s[38:39], 0x17000
	s_mov_b64 s[40:41], 0x17800
	s_mov_b64 s[42:43], 0x47000
	s_mov_b64 s[44:45], 0x47800
	s_mov_b64 s[46:47], 0x4f000
	s_mov_b64 s[48:49], 0x4f800
	s_mov_b64 s[50:51], 0x57000
	s_mov_b64 s[52:53], 0x57800
	s_barrier
	s_branch .LBB0_2012

.LBB0_2108:
	s_mov_b64 s[16:17], 0x80
	s_and_b32 s6, s4, 3
	s_add_i32 m0, s37, 0x18000
	v_lshl_add_u64 v[8:9], v[8:9], 0, s[16:17]
	s_lshl_b32 s7, s1, 13
	s_lshl_b32 s11, s6, 12
	global_load_lds_dwordx4 v[8:9], off
	v_lshl_add_u64 v[4:5], v[4:5], 0, s[16:17]
	s_add_i32 m0, s37, 0x1a000
	s_add_i32 s50, s37, 0x8000
	s_add_i32 s51, s37, 0xa000
	global_load_lds_dwordx4 v[4:5], off
	v_lshl_add_u64 v[2:3], v[2:3], 0, s[16:17]
	s_mov_b32 m0, s50
	s_add_u32 s4, s2, 0x40080
	global_load_lds_dwordx4 v[2:3], off
	v_lshl_add_u64 v[2:3], v[6:7], 0, s[16:17]
	s_mov_b32 m0, s51
	s_addc_u32 s5, s3, 0
	global_load_lds_dwordx4 v[2:3], off
	s_add_i32 m0, s37, 0x1c000
	v_lshl_add_u64 v[2:3], s[4:5], 0, v[156:157]
	global_load_lds_dwordx4 v[2:3], off
	v_lshl_add_u64 v[2:3], s[4:5], 0, v[160:161]
	s_add_i32 m0, s37, 0x1e000
	s_cmpk_lt_u32 s0, 0x100
	global_load_lds_dwordx4 v[2:3], off
	v_bfe_u32 v2, v0, 4, 2
	v_and_b32_e32 v3, 15, v0
	v_lshl_or_b32 v1, s1, 6, v3
	v_lshlrev_b32_e32 v4, 3, v2
	v_lshlrev_b32_e32 v5, 4, v2
	v_cmp_eq_u32_e64 s[4:5], 0, v2
	v_lshlrev_b32_e32 v2, 8, v0
	v_lshlrev_b32_e32 v6, 2, v1
	v_lshl_or_b32 v183, s6, 5, v4
	v_and_b32_e32 v2, 0x18000, v2
	v_lshlrev_b32_e32 v4, 11, v12
	v_lshl_or_b32 v3, v3, 6, v5
	v_and_b32_e32 v7, 32, v6
	v_or3_b32 v2, v10, v2, v4
	v_bitop3_b32 v3, v3, s7, v7 bitop3:0xde
	v_lshlrev_b32_e32 v7, 6, v0
	s_movk_i32 s1, 0x3c0
	v_add_u32_e32 v162, v2, v11
	v_lshlrev_b32_e32 v2, 4, v13
	v_and_or_b32 v5, v7, s1, v5
	v_lshlrev_b32_e32 v7, 2, v0
	v_and_b32_e32 v2, 0x38000, v2
	v_and_b32_e32 v8, 32, v7
	s_waitcnt vmcnt(8)
	s_barrier
	s_waitcnt vmcnt(6)
	s_cselect_b64 s[18:19], -1, 0
	s_lshl_b32 s0, s6, 10
	s_add_i32 s1, 0, 0x20000
	v_or3_b32 v2, v10, v2, v4
	v_bitop3_b32 v182, s11, v5, v8 bitop3:0xf6
	s_add_i32 s0, s1, s0
	v_add_u32_e32 v164, v2, v11
	s_add_i32 s54, 0, 0x10000
	s_add_i32 s55, 0, 0x14000
	v_mbcnt_lo_u32_b32 v2, -1, 0
	s_ashr_i32 s52, s75, 31
	s_ashr_i32 s53, s64, 31
	v_add_u32_e32 v184, s0, v6
	v_add_u32_e32 v185, s1, v7
	v_mov_b32_e32 v163, v157
	v_mov_b32_e32 v165, v157
	v_mov_b64_e32 v[166:167], 0x100
	v_mov_b64_e32 v[168:169], 0xff
	v_add_u32_e32 v186, s54, v182
	v_add_u32_e32 v187, s55, v182
	v_add_u32_e32 v188, 0, v3
	v_mbcnt_hi_u32_b32 v189, -1, v2
	s_mov_b64 s[20:21], 0x48000
	s_mov_b64 s[22:23], 0x50000
	s_mov_b64 s[24:25], 0x58000
	s_barrier
	s_branch .LBB0_2111

.LBB0_2201:
	s_add_u32 s12, s72, 0x9400000
	s_addc_u32 s13, s73, 0
	s_lshl_b32 s5, s5, 5
	s_mov_b64 s[14:15], 0x80
	s_and_b32 s5, s5, 0x60
	s_add_i32 m0, s27, 0x18000
	v_lshl_add_u64 v[10:11], v[10:11], 0, s[14:15]
	s_lshl_b32 s8, s1, 13
	s_lshl_b32 s18, s5, 7
	global_load_lds_dwordx4 v[10:11], off
	v_lshl_add_u64 v[8:9], v[8:9], 0, s[14:15]
	s_add_i32 m0, s27, 0x1a000
	s_add_i32 s41, s27, 0x8000
	s_add_i32 s42, s27, 0xa000
	global_load_lds_dwordx4 v[8:9], off
	v_lshl_add_u64 v[4:5], v[4:5], 0, s[14:15]
	s_mov_b32 m0, s41
	s_add_u32 s16, s2, 0x40080
	global_load_lds_dwordx4 v[4:5], off
	v_lshl_add_u64 v[4:5], v[6:7], 0, s[14:15]
	s_mov_b32 m0, s42
	s_addc_u32 s17, s3, 0
	global_load_lds_dwordx4 v[4:5], off
	s_add_i32 m0, s27, 0x1c000
	v_lshl_add_u64 v[4:5], s[16:17], 0, v[134:135]
	global_load_lds_dwordx4 v[4:5], off
	v_lshl_add_u64 v[4:5], s[16:17], 0, v[130:131]
	s_add_i32 m0, s27, 0x1e000
	v_lshlrev_b32_e32 v6, 2, v0
	global_load_lds_dwordx4 v[4:5], off
	v_and_b32_e32 v4, 15, v0
	v_lshl_or_b32 v1, s1, 6, v4
	v_lshlrev_b32_e32 v5, 1, v2
	v_lshlrev_b32_e32 v7, 6, v0
	s_movk_i32 s1, 0x3c0
	v_lshl_or_b32 v4, v4, 6, v5
	v_and_b32_e32 v6, 32, v6
	v_and_or_b32 v5, v7, s1, v5
	v_bitop3_b32 v164, s18, v5, v6 bitop3:0xf6
	v_lshlrev_b32_e32 v5, 8, v0
	v_lshlrev_b32_e32 v3, 4, v3
	v_bitop3_b32 v4, v4, s8, v6 bitop3:0xde
	s_waitcnt vmcnt(8)
	s_barrier
	s_waitcnt vmcnt(6)
	s_cmpk_lt_u32 s0, 0x100
	v_and_b32_e32 v5, 0x18000, v5
	v_lshlrev_b32_e32 v6, 11, v14
	v_and_b32_e32 v3, 0x38000, v3
	s_cselect_b64 s[16:17], -1, 0
	v_or3_b32 v5, v12, v5, v6
	v_or3_b32 v3, v12, v3, v6
	s_add_i32 s44, 0, 0x10000
	s_add_i32 s45, 0, 0x14000
	s_sext_i32_i8 s48, s4
	s_ashr_i32 s43, s75, 31
	v_add_u32_e32 v140, v5, v13
	v_mov_b32_e32 v141, v139
	v_add_u32_e32 v142, v3, v13
	v_mov_b32_e32 v143, v139
	v_mov_b64_e32 v[144:145], 0x580
	v_mov_b64_e32 v[146:147], 0x57f
	v_add_u32_e32 v165, s44, v164
	v_add_u32_e32 v166, s45, v164
	v_add_u32_e32 v167, 0, v4
	v_mov_b32_e32 v168, 0x358637bd
	s_movk_i32 s46, 0x1600
	s_lshl_b32 s8, s5, 1
	v_lshlrev_b32_e32 v138, 1, v2
	s_mov_b32 s47, s9
	s_barrier
	s_branch .LBB0_2204

.LBB0_2276:
	s_lshl_b32 s7, s7, 5
	s_mov_b64 s[10:11], 0x80
	s_and_b32 s7, s7, 0x60
	s_add_i32 m0, s26, 0x18000
	v_lshl_add_u64 v[8:9], v[8:9], 0, s[10:11]
	s_lshl_b32 s14, s5, 13
	s_lshl_b32 s15, s7, 7
	global_load_lds_dwordx4 v[8:9], off
	v_lshl_add_u64 v[6:7], v[6:7], 0, s[10:11]
	s_add_i32 m0, s26, 0x1a000
	s_add_i32 s31, s26, 0x8000
	s_add_i32 s33, s26, 0xa000
	global_load_lds_dwordx4 v[6:7], off
	v_lshl_add_u64 v[2:3], v[2:3], 0, s[10:11]
	s_mov_b32 m0, s31
	s_add_u32 s12, s2, 0xb0080
	global_load_lds_dwordx4 v[2:3], off
	v_lshl_add_u64 v[2:3], v[4:5], 0, s[10:11]
	s_mov_b32 m0, s33
	s_addc_u32 s13, s3, 0
	global_load_lds_dwordx4 v[2:3], off
	s_add_i32 m0, s26, 0x1c000
	v_lshl_add_u64 v[2:3], s[12:13], 0, v[130:131]
	global_load_lds_dwordx4 v[2:3], off
	v_lshl_add_u64 v[2:3], s[12:13], 0, v[134:135]
	s_add_i32 m0, s26, 0x1e000
	v_lshlrev_b32_e32 v4, 2, v0
	global_load_lds_dwordx4 v[2:3], off
	v_and_b32_e32 v2, 15, v0
	v_lshl_or_b32 v150, s5, 6, v2
	v_lshlrev_b32_e32 v3, 1, v11
	v_lshlrev_b32_e32 v0, 6, v0
	s_movk_i32 s5, 0x3c0
	v_and_b32_e32 v4, 32, v4
	v_and_or_b32 v0, v0, s5, v3
	v_lshl_or_b32 v2, v2, 6, v3
	v_bitop3_b32 v151, s15, v0, v4 bitop3:0xf6
	s_waitcnt vmcnt(8)
	s_barrier
	s_waitcnt vmcnt(6)
	s_cmpk_lt_u32 s4, 0x100
	v_add_u16_e32 v0, v1, v10
	v_bitop3_b32 v2, v2, s14, v4 bitop3:0xde
	s_cselect_b64 s[12:13], -1, 0
	v_lshrrev_b16_e32 v0, 1, v0
	s_add_i32 s35, 0, 0x10000
	s_add_i32 s36, 0, 0x14000
	s_sext_i32_i8 s40, s6
	s_ashr_i32 s34, s75, 31
	v_or_b32_e32 v152, s7, v11
	v_add_lshl_u32 v136, v12, v0, 1
	v_mov_b32_e32 v137, v131
	v_add_lshl_u32 v138, v13, v0, 1
	v_mov_b32_e32 v139, v131
	v_mov_b64_e32 v[140:141], 0x100
	v_mov_b64_e32 v[142:143], 0xff
	v_add_u32_e32 v153, s35, v151
	v_add_u32_e32 v154, s36, v151
	v_add_u32_e32 v155, 0, v2
	s_barrier
	s_branch .LBB0_2279
